# ctx pass start waits on LDS only, so the local V^T LDS-DMA stays in flight under the ctx pass
# speedup vs baseline: 1.0241x; 1.0110x over previous
; #define AH_LDK(c, bufi) do { kf[bufi][0] = *(const LAS bf16x8*)(lds + kaddr0 + (c) * kcs); kf[bufi][1] = *(const LAS bf16x8*)(lds + kaddr1 + (c) * kcs); \
;         kf[bufi][2] = *(const LAS bf16x8*)(lds + kaddr0 + (c) * kcs + 512); kf[bufi][3] = *(const LAS bf16x8*)(lds + kaddr1 + (c) * kcs + 512); } while (0)
; template <bool LOC> ...
;     ...
;     AH_LDK(0, 0);
; #pragma unroll
;     for (int c = 0; c < 8; ++c) {
;         if (c < 7) AH_LDK(c + 1, (c + 1) & 1);
;         __builtin_amdgcn_sched_barrier(0);
;         f32x4 t0 = (f32x4){0.f, 0.f, 0.f, 0.f}, t1 = (f32x4){0.f, 0.f, 0.f, 0.f};
;         t0 = __builtin_amdgcn_mfma_f32_16x16x32_bf16(kf[c & 1][0], q0, t0, 0, 0, 0); t1 = __builtin_amdgcn_mfma_f32_16x16x32_bf16(kf[c & 1][2], q0, t1, 0, 0, 0);
;         t0 = __builtin_amdgcn_mfma_f32_16x16x32_bf16(kf[c & 1][1], q1, t0, 0, 0, 0); t1 = __builtin_amdgcn_mfma_f32_16x16x32_bf16(kf[c & 1][3], q1, t1, 0, 0, 0);
; #pragma unroll
;         for (int e = 0; e < 8; ++e) { const float a = (e < 4) ? t0[e] : t1[e - 4];
;             if (LOC) { const float bv = bp[c * RPB_PITCH + e]; const bool ok = (e >= elo) && (e < elo + 16); s[c][e] = ok ? (a * SC + bv) : -INFINITY; }
;             else s[c][e] = a * SC; }
;         __builtin_amdgcn_sched_barrier(0);
;     }
;     ...
;     float m2 = mx;
; #pragma unroll
;     for (int c = 0; c < 8; ++c)
; #pragma unroll
;         for (int e = 0; e < 8; ++e) m2 = fmaxf(m2, s[c][e]);
;     m2 = fmaxf(m2, __shfl_xor(m2, 16)); m2 = fmaxf(m2, __shfl_xor(m2, 32));
;     const float alpha = __builtin_amdgcn_exp2f(mx - m2);
; __device__ __forceinline__ void phase_mixer(const Params& p, LAS unsigned char* lds, int l, bool with_ctx, int G, int tid, int wave, int lane, int rep_attn, int rep_pool) {
;     ...
;                 const int qtok = (ps == 1) ? (b * SEQ + r * 64 + 16 * n + qi) : (ML + b * CT + 16 * (sel * 8 + wave) + qi);
;                 const bf16_t* qp = PB + (size_t)qtok * PBW + 512 + h * 64 + 8 * g;
;                 qA0 = *(const bf16x8*)qp; qA1 = *(const bf16x8*)(qp + 32);
;                 mxA = -INFINITY; lA = 0.f;
; #pragma unroll
;                 for (int dt = 0; dt < 4; ++dt) oA[dt] = (f32x4){0.f, 0.f, 0.f, 0.f};
;                 attn_half<false>(lds, ka0, ka1, 32 * 128, vrow, 0, 4, 16 * 512, nullptr, 0, qA0, qA1, mxA, lA, oA, g, qi);
.Lqjoin_299:
	ds_read_b128 v[8:11], v132
	ds_read_b128 v[12:15], v132 offset:512
	ds_read_b128 v[16:19], v133
	ds_read_b128 v[20:23], v133 offset:512
	ds_read_b128 v[24:27], v132 offset:4096
	ds_read_b128 v[28:31], v132 offset:4608
	ds_read_b128 v[32:35], v133 offset:4096
	ds_read_b128 v[36:39], v133 offset:4608
	s_waitcnt lgkmcnt(7)
	v_mfma_f32_16x16x32_bf16 v[8:11], v[8:11], v[4:7], 0
	s_waitcnt lgkmcnt(5)
	v_mfma_f32_16x16x32_bf16 v[68:71], v[16:19], v[0:3], v[8:11]
	v_mfma_f32_16x16x32_bf16 v[8:11], v[12:15], v[4:7], 0
	s_waitcnt lgkmcnt(4)
	v_mfma_f32_16x16x32_bf16 v[64:67], v[20:23], v[0:3], v[8:11]
	s_nop 4
	ds_read_b128 v[8:11], v132 offset:8192
	ds_read_b128 v[12:15], v132 offset:8704
	ds_read_b128 v[16:19], v133 offset:8192
	ds_read_b128 v[20:23], v133 offset:8704
	s_waitcnt lgkmcnt(4)
	v_mfma_f32_16x16x32_bf16 v[24:27], v[24:27], v[4:7], 0
	v_mfma_f32_16x16x32_bf16 v[60:63], v[32:35], v[0:3], v[24:27]
	v_mfma_f32_16x16x32_bf16 v[24:27], v[28:31], v[4:7], 0
	v_mfma_f32_16x16x32_bf16 v[56:59], v[36:39], v[0:3], v[24:27]
	s_nop 4
	ds_read_b128 v[24:27], v132 offset:12288
	ds_read_b128 v[28:31], v132 offset:12800
	ds_read_b128 v[32:35], v133 offset:12288
	ds_read_b128 v[36:39], v133 offset:12800
	s_waitcnt lgkmcnt(4)
	v_mfma_f32_16x16x32_bf16 v[8:11], v[8:11], v[4:7], 0
	v_mfma_f32_16x16x32_bf16 v[52:55], v[16:19], v[0:3], v[8:11]
	v_mfma_f32_16x16x32_bf16 v[8:11], v[12:15], v[4:7], 0
	v_mfma_f32_16x16x32_bf16 v[48:51], v[20:23], v[0:3], v[8:11]
	s_nop 4
	ds_read_b128 v[8:11], v132 offset:16384
	ds_read_b128 v[12:15], v132 offset:16896
	ds_read_b128 v[16:19], v133 offset:16384
	ds_read_b128 v[20:23], v133 offset:16896
	s_waitcnt lgkmcnt(4)
	v_mfma_f32_16x16x32_bf16 v[24:27], v[24:27], v[4:7], 0
	v_mfma_f32_16x16x32_bf16 v[44:47], v[32:35], v[0:3], v[24:27]
	v_mfma_f32_16x16x32_bf16 v[24:27], v[28:31], v[4:7], 0
	v_mfma_f32_16x16x32_bf16 v[40:43], v[36:39], v[0:3], v[24:27]
	s_nop 4
	ds_read_b128 v[24:27], v132 offset:20480
	ds_read_b128 v[152:155], v132 offset:20992
	ds_read_b128 v[28:31], v133 offset:20480
	ds_read_b128 v[170:173], v133 offset:20992
	s_waitcnt lgkmcnt(4)
	v_mfma_f32_16x16x32_bf16 v[8:11], v[8:11], v[4:7], 0
	v_mfma_f32_16x16x32_bf16 v[36:39], v[16:19], v[0:3], v[8:11]
	v_mfma_f32_16x16x32_bf16 v[8:11], v[12:15], v[4:7], 0
	v_mfma_f32_16x16x32_bf16 v[32:35], v[20:23], v[0:3], v[8:11]
	s_nop 4
	ds_read_b128 v[8:11], v132 offset:24576
	ds_read_b128 v[12:15], v132 offset:25088
	ds_read_b128 v[16:19], v133 offset:24576
	ds_read_b128 v[174:177], v133 offset:25088
	s_waitcnt lgkmcnt(4)
	v_mfma_f32_16x16x32_bf16 v[20:23], v[24:27], v[4:7], 0
	v_mfma_f32_16x16x32_bf16 v[28:31], v[28:31], v[0:3], v[20:23]
	v_mfma_f32_16x16x32_bf16 v[20:23], v[152:155], v[4:7], 0
	v_mfma_f32_16x16x32_bf16 v[24:27], v[170:173], v[0:3], v[20:23]
	s_nop 4
	ds_read_b128 v[152:155], v132 offset:28672
	ds_read_b128 v[170:173], v132 offset:29184
	ds_read_b128 v[178:181], v133 offset:28672
	ds_read_b128 v[182:185], v133 offset:29184
	s_waitcnt lgkmcnt(0)
	v_mfma_f32_16x16x32_bf16 v[8:11], v[8:11], v[4:7], 0
	v_mfma_f32_16x16x32_bf16 v[20:23], v[16:19], v[0:3], v[8:11]
	v_mfma_f32_16x16x32_bf16 v[8:11], v[12:15], v[4:7], 0
	v_mfma_f32_16x16x32_bf16 v[16:19], v[174:177], v[0:3], v[8:11]
	s_nop 4
	v_mfma_f32_16x16x32_bf16 v[8:11], v[152:155], v[4:7], 0
	v_mfma_f32_16x16x32_bf16 v[12:15], v[178:181], v[0:3], v[8:11]
	v_mfma_f32_16x16x32_bf16 v[8:11], v[170:173], v[4:7], 0
	v_mfma_f32_16x16x32_bf16 v[8:11], v[182:185], v[0:3], v[8:11]
	s_nop 4
	s_mov_b32 s30, 0xff800000
	v_max3_f32 v97, v68, s30, v69
	v_max3_f32 v97, v97, v70, v71
	v_max3_f32 v97, v97, v64, v65
	v_max3_f32 v97, v97, v66, v67
	v_max3_f32 v97, v97, v60, v61
	v_max3_f32 v97, v97, v62, v63
	v_max3_f32 v97, v97, v56, v57
	v_max3_f32 v97, v97, v58, v59
	v_max3_f32 v97, v97, v52, v53
	v_max3_f32 v97, v97, v54, v55
	v_max3_f32 v97, v97, v48, v49
	v_max3_f32 v97, v97, v50, v51
	v_max3_f32 v97, v97, v44, v45
	v_max3_f32 v97, v97, v46, v47
	v_max3_f32 v97, v97, v40, v41
	v_max3_f32 v97, v97, v42, v43
	v_max3_f32 v97, v97, v36, v37
	v_max3_f32 v97, v97, v38, v39
	v_max3_f32 v97, v97, v32, v33
	v_max3_f32 v97, v97, v34, v35
	v_max3_f32 v97, v97, v28, v29
	v_max3_f32 v97, v97, v30, v31
	v_max3_f32 v97, v97, v24, v25
	v_max3_f32 v97, v97, v26, v27
	v_max3_f32 v97, v97, v20, v21
	v_max3_f32 v97, v97, v22, v23
	v_max3_f32 v97, v97, v16, v17
	v_max3_f32 v97, v97, v18, v19
	v_max3_f32 v97, v97, v12, v13
	v_max3_f32 v97, v97, v14, v15
	v_max3_f32 v97, v97, v8, v9
	v_max3_f32 v97, v97, v10, v11
	v_mul_f32_e32 v97, 0x3e38aa3b, v97
	ds_bpermute_b32 v99, v114, v97
	ds_read_b128 v[152:155], v134 offset:32768
	ds_read_b128 v[170:173], v134 offset:40960
	ds_read_b128 v[174:177], v134 offset:49152
	ds_read_b128 v[178:181], v134 offset:57344
	ds_read_b128 v[182:185], v135 offset:32768
	ds_read_b128 v[186:189], v135 offset:40960
	ds_read_b128 v[190:193], v135 offset:49152
	ds_read_b128 v[194:197], v135 offset:57344
	s_waitcnt lgkmcnt(8)
	v_max_f32_e32 v99, v99, v99
	v_max_f32_e32 v97, v97, v99
	ds_bpermute_b32 v99, v115, v97
	s_waitcnt lgkmcnt(0)
; __device__ __forceinline__ unsigned cvt_pk_bf16(float lo, float hi) { const f32x2 v = (f32x2){lo, hi}; return __builtin_bit_cast(unsigned, __builtin_convertvector(v, bf16v2)); }
; #define AH_LDV(c, bufi) do { const int vaddr = vrow + (((vchunk0 + (c) * vcs + g) ^ qi) << 4); _Pragma("unroll") for (int dt = 0; dt < 4; ++dt) vf[bufi][dt] = *(const LAS bf16x8*)(lds + vaddr + dt * vpitch_dt); } while (0)
; template <bool LOC> ...
;     ...
;     const float alpha = __builtin_amdgcn_exp2f(mx - m2);
;     mx = m2; lsum *= alpha;
; #pragma unroll
;     for (int dt = 0; dt < 4; ++dt) o[dt] = o[dt] * alpha;
;     bf16x8 vf[2][4];
;     ...
;     AH_LDV(0, 0);
; #pragma unroll
;     for (int c = 0; c < 8; ++c) {
;         if (c < 7) AH_LDV(c + 1, (c + 1) & 1);
;         __builtin_amdgcn_sched_barrier(0);
;         float pe[8];
; #pragma unroll
;         for (int e = 0; e < 8; ++e) { pe[e] = __builtin_amdgcn_exp2f(s[c][e] - mx); lsum += pe[e]; }
;         u32x4 pw; pw.x = cvt_pk_bf16(pe[0], pe[1]); pw.y = cvt_pk_bf16(pe[2], pe[3]); pw.z = cvt_pk_bf16(pe[4], pe[5]); pw.w = cvt_pk_bf16(pe[6], pe[7]);
;         const bf16x8 pb = __builtin_bit_cast(bf16x8, pw);
; #pragma unroll
;         for (int dt = 0; dt < 4; ++dt) o[dt] = __builtin_amdgcn_mfma_f32_16x16x32_bf16(vf[c & 1][dt], pb, o[dt], 0, 0, 0);
;         __builtin_amdgcn_sched_barrier(0);
;     }
	v_max_f32_e32 v99, v99, v99
	v_max_f32_e32 v97, v97, v99
	v_sub_f32_e32 v99, 0xff800000, v97
	v_exp_f32_e32 v99, v99
	s_nop 0
	v_mul_f32_e32 v198, 0, v99
	v_mov_b32_e32 v199, v198
	v_mov_b32_e32 v200, v198
	v_mov_b32_e32 v201, v198
	v_mov_b32_e32 v206, v97
	v_mov_b32_e32 v207, v97
	v_mov_b32_e32 v208, s67
	v_mov_b32_e32 v209, s67
	v_mov_b32_e32 v210, 0
	v_mov_b32_e32 v211, 0
	v_pk_fma_f32 v[68:69], v[68:69], v[208:209], v[206:207] neg_lo:[0,0,1] neg_hi:[0,0,1]
	v_pk_fma_f32 v[70:71], v[70:71], v[208:209], v[206:207] neg_lo:[0,0,1] neg_hi:[0,0,1]
	v_exp_f32_e32 v68, v68
	v_pk_fma_f32 v[64:65], v[64:65], v[208:209], v[206:207] neg_lo:[0,0,1] neg_hi:[0,0,1]
	v_exp_f32_e32 v69, v69
	v_pk_fma_f32 v[66:67], v[66:67], v[208:209], v[206:207] neg_lo:[0,0,1] neg_hi:[0,0,1]
	v_exp_f32_e32 v70, v70
	v_exp_f32_e32 v71, v71
	v_exp_f32_e32 v212, v64
	v_pk_add_f32 v[210:211], v[210:211], v[68:69]
	v_exp_f32_e32 v213, v65
	v_pk_add_f32 v[210:211], v[210:211], v[70:71]
	v_exp_f32_e32 v214, v66
	v_exp_f32_e32 v215, v67
	v_pk_add_f32 v[210:211], v[210:211], v[212:213]
	v_cvt_pk_bf16_f32 v64, v68, v69
	v_pk_add_f32 v[210:211], v[210:211], v[214:215]
	v_cvt_pk_bf16_f32 v65, v70, v71
	v_cvt_pk_bf16_f32 v66, v212, v213
	v_cvt_pk_bf16_f32 v67, v214, v215
	s_nop 1
	v_mfma_f32_16x16x32_bf16 v[68:71], v[152:155], v[64:67], v[198:201]
	v_mfma_f32_16x16x32_bf16 v[152:155], v[170:173], v[64:67], v[198:201]
	v_mfma_f32_16x16x32_bf16 v[170:173], v[174:177], v[64:67], v[198:201]
	v_mfma_f32_16x16x32_bf16 v[64:67], v[178:181], v[64:67], v[198:201]
	ds_read_b128 v[174:177], v136 offset:32768
	ds_read_b128 v[178:181], v136 offset:40960
	s_nop 0
	ds_read_b128 v[198:201], v136 offset:49152
	ds_read_b128 v[202:205], v136 offset:57344
	v_pk_fma_f32 v[60:61], v[60:61], v[208:209], v[206:207] neg_lo:[0,0,1] neg_hi:[0,0,1]
	v_pk_fma_f32 v[62:63], v[62:63], v[208:209], v[206:207] neg_lo:[0,0,1] neg_hi:[0,0,1]
	v_exp_f32_e32 v60, v60
	v_pk_fma_f32 v[56:57], v[56:57], v[208:209], v[206:207] neg_lo:[0,0,1] neg_hi:[0,0,1]
	v_exp_f32_e32 v61, v61
	v_pk_fma_f32 v[58:59], v[58:59], v[208:209], v[206:207] neg_lo:[0,0,1] neg_hi:[0,0,1]
	v_exp_f32_e32 v62, v62
	v_exp_f32_e32 v63, v63
	v_exp_f32_e32 v212, v56
	v_pk_add_f32 v[210:211], v[210:211], v[60:61]
	v_exp_f32_e32 v213, v57
	v_pk_add_f32 v[210:211], v[210:211], v[62:63]
	v_exp_f32_e32 v214, v58
	v_exp_f32_e32 v215, v59
	v_pk_add_f32 v[210:211], v[210:211], v[212:213]
	v_cvt_pk_bf16_f32 v56, v60, v61
	v_pk_add_f32 v[210:211], v[210:211], v[214:215]
	v_cvt_pk_bf16_f32 v57, v62, v63
	v_cvt_pk_bf16_f32 v58, v212, v213
	v_cvt_pk_bf16_f32 v59, v214, v215
	s_nop 1
	v_mfma_f32_16x16x32_bf16 v[60:63], v[182:185], v[56:59], v[68:71]
	v_mfma_f32_16x16x32_bf16 v[68:71], v[186:189], v[56:59], v[152:155]
	v_mfma_f32_16x16x32_bf16 v[152:155], v[190:193], v[56:59], v[170:173]
	v_mfma_f32_16x16x32_bf16 v[56:59], v[194:197], v[56:59], v[64:67]
	s_nop 2
	ds_read_b128 v[64:67], v137 offset:32768
	ds_read_b128 v[170:173], v137 offset:40960
	ds_read_b128 v[182:185], v137 offset:49152
	ds_read_b128 v[186:189], v137 offset:57344
	v_pk_fma_f32 v[52:53], v[52:53], v[208:209], v[206:207] neg_lo:[0,0,1] neg_hi:[0,0,1]
	v_pk_fma_f32 v[54:55], v[54:55], v[208:209], v[206:207] neg_lo:[0,0,1] neg_hi:[0,0,1]
	v_exp_f32_e32 v52, v52
	v_pk_fma_f32 v[48:49], v[48:49], v[208:209], v[206:207] neg_lo:[0,0,1] neg_hi:[0,0,1]
	v_exp_f32_e32 v53, v53
	v_pk_fma_f32 v[50:51], v[50:51], v[208:209], v[206:207] neg_lo:[0,0,1] neg_hi:[0,0,1]
	v_exp_f32_e32 v54, v54
	v_exp_f32_e32 v55, v55
	v_exp_f32_e32 v212, v48
	v_pk_add_f32 v[210:211], v[210:211], v[52:53]
	v_exp_f32_e32 v213, v49
	v_pk_add_f32 v[210:211], v[210:211], v[54:55]
	v_exp_f32_e32 v214, v50
	v_exp_f32_e32 v215, v51
	v_pk_add_f32 v[210:211], v[210:211], v[212:213]
	v_cvt_pk_bf16_f32 v48, v52, v53
	v_pk_add_f32 v[210:211], v[210:211], v[214:215]
	v_cvt_pk_bf16_f32 v49, v54, v55
	v_cvt_pk_bf16_f32 v50, v212, v213
	v_cvt_pk_bf16_f32 v51, v214, v215
	s_waitcnt lgkmcnt(4)
	s_nop 0
	v_mfma_f32_16x16x32_bf16 v[52:55], v[174:177], v[48:51], v[60:63]
	v_mfma_f32_16x16x32_bf16 v[60:63], v[178:181], v[48:51], v[68:71]
	v_mfma_f32_16x16x32_bf16 v[68:71], v[198:201], v[48:51], v[152:155]
	v_mfma_f32_16x16x32_bf16 v[48:51], v[202:205], v[48:51], v[56:59]
	s_nop 2
	ds_read_b128 v[56:59], v138 offset:32768
	ds_read_b128 v[152:155], v138 offset:40960
	ds_read_b128 v[174:177], v138 offset:49152
	ds_read_b128 v[178:181], v138 offset:57344
	v_pk_fma_f32 v[44:45], v[44:45], v[208:209], v[206:207] neg_lo:[0,0,1] neg_hi:[0,0,1]
	v_pk_fma_f32 v[46:47], v[46:47], v[208:209], v[206:207] neg_lo:[0,0,1] neg_hi:[0,0,1]
	v_exp_f32_e32 v44, v44
	v_pk_fma_f32 v[40:41], v[40:41], v[208:209], v[206:207] neg_lo:[0,0,1] neg_hi:[0,0,1]
	v_exp_f32_e32 v45, v45
	v_pk_fma_f32 v[42:43], v[42:43], v[208:209], v[206:207] neg_lo:[0,0,1] neg_hi:[0,0,1]
	v_exp_f32_e32 v46, v46
	v_exp_f32_e32 v47, v47
	v_exp_f32_e32 v212, v40
	v_pk_add_f32 v[210:211], v[210:211], v[44:45]
	v_exp_f32_e32 v213, v41
	v_pk_add_f32 v[210:211], v[210:211], v[46:47]
	v_exp_f32_e32 v214, v42
	v_exp_f32_e32 v215, v43
	v_pk_add_f32 v[210:211], v[210:211], v[212:213]
	v_cvt_pk_bf16_f32 v40, v44, v45
	v_pk_add_f32 v[210:211], v[210:211], v[214:215]
	v_cvt_pk_bf16_f32 v41, v46, v47
	v_cvt_pk_bf16_f32 v42, v212, v213
	v_cvt_pk_bf16_f32 v43, v214, v215
	s_waitcnt lgkmcnt(4)
; __device__ __forceinline__ unsigned cvt_pk_bf16(float lo, float hi) { const f32x2 v = (f32x2){lo, hi}; return __builtin_bit_cast(unsigned, __builtin_convertvector(v, bf16v2)); }
; #define AH_LDV(c, bufi) do { const int vaddr = vrow + (((vchunk0 + (c) * vcs + g) ^ qi) << 4); _Pragma("unroll") for (int dt = 0; dt < 4; ++dt) vf[bufi][dt] = *(const LAS bf16x8*)(lds + vaddr + dt * vpitch_dt); } while (0)
; template <bool LOC> ...
;     ...
;     for (int c = 0; c < 8; ++c) {
;         if (c < 7) AH_LDV(c + 1, (c + 1) & 1);
;         __builtin_amdgcn_sched_barrier(0);
;         float pe[8];
; #pragma unroll
;         for (int e = 0; e < 8; ++e) { pe[e] = __builtin_amdgcn_exp2f(s[c][e] - mx); lsum += pe[e]; }
;         u32x4 pw; pw.x = cvt_pk_bf16(pe[0], pe[1]); pw.y = cvt_pk_bf16(pe[2], pe[3]); pw.z = cvt_pk_bf16(pe[4], pe[5]); pw.w = cvt_pk_bf16(pe[6], pe[7]);
;         const bf16x8 pb = __builtin_bit_cast(bf16x8, pw);
; #pragma unroll
;         for (int dt = 0; dt < 4; ++dt) o[dt] = __builtin_amdgcn_mfma_f32_16x16x32_bf16(vf[c & 1][dt], pb, o[dt], 0, 0, 0);
;         __builtin_amdgcn_sched_barrier(0);
;     }
	s_nop 0
	v_mfma_f32_16x16x32_bf16 v[44:47], v[64:67], v[40:43], v[52:55]
	v_mfma_f32_16x16x32_bf16 v[52:55], v[170:173], v[40:43], v[60:63]
	v_mfma_f32_16x16x32_bf16 v[60:63], v[182:185], v[40:43], v[68:71]
	v_mfma_f32_16x16x32_bf16 v[40:43], v[186:189], v[40:43], v[48:51]
	s_nop 2
	ds_read_b128 v[48:51], v139 offset:32768
	ds_read_b128 v[64:67], v139 offset:40960
	ds_read_b128 v[68:71], v139 offset:49152
	ds_read_b128 v[170:173], v139 offset:57344
	v_pk_fma_f32 v[36:37], v[36:37], v[208:209], v[206:207] neg_lo:[0,0,1] neg_hi:[0,0,1]
	v_pk_fma_f32 v[38:39], v[38:39], v[208:209], v[206:207] neg_lo:[0,0,1] neg_hi:[0,0,1]
	v_exp_f32_e32 v36, v36
	v_pk_fma_f32 v[32:33], v[32:33], v[208:209], v[206:207] neg_lo:[0,0,1] neg_hi:[0,0,1]
	v_exp_f32_e32 v37, v37
	v_pk_fma_f32 v[34:35], v[34:35], v[208:209], v[206:207] neg_lo:[0,0,1] neg_hi:[0,0,1]
	v_exp_f32_e32 v38, v38
	v_exp_f32_e32 v39, v39
	v_exp_f32_e32 v212, v32
	v_pk_add_f32 v[210:211], v[210:211], v[36:37]
	v_exp_f32_e32 v213, v33
	v_pk_add_f32 v[210:211], v[210:211], v[38:39]
	v_exp_f32_e32 v214, v34
	v_exp_f32_e32 v215, v35
	v_pk_add_f32 v[210:211], v[210:211], v[212:213]
	v_cvt_pk_bf16_f32 v32, v36, v37
	v_pk_add_f32 v[210:211], v[210:211], v[214:215]
	v_cvt_pk_bf16_f32 v33, v38, v39
	v_cvt_pk_bf16_f32 v34, v212, v213
	v_cvt_pk_bf16_f32 v35, v214, v215
	s_waitcnt lgkmcnt(4)
	s_nop 0
	v_mfma_f32_16x16x32_bf16 v[36:39], v[56:59], v[32:35], v[44:47]
	v_mfma_f32_16x16x32_bf16 v[44:47], v[152:155], v[32:35], v[52:55]
	v_mfma_f32_16x16x32_bf16 v[52:55], v[174:177], v[32:35], v[60:63]
	v_mfma_f32_16x16x32_bf16 v[32:35], v[178:181], v[32:35], v[40:43]
	s_nop 2
	ds_read_b128 v[40:43], v140 offset:32768
	ds_read_b128 v[56:59], v140 offset:40960
	ds_read_b128 v[60:63], v140 offset:49152
	ds_read_b128 v[152:155], v140 offset:57344
	v_pk_fma_f32 v[28:29], v[28:29], v[208:209], v[206:207] neg_lo:[0,0,1] neg_hi:[0,0,1]
	v_pk_fma_f32 v[30:31], v[30:31], v[208:209], v[206:207] neg_lo:[0,0,1] neg_hi:[0,0,1]
	v_exp_f32_e32 v28, v28
	v_pk_fma_f32 v[24:25], v[24:25], v[208:209], v[206:207] neg_lo:[0,0,1] neg_hi:[0,0,1]
	v_exp_f32_e32 v29, v29
	v_pk_fma_f32 v[26:27], v[26:27], v[208:209], v[206:207] neg_lo:[0,0,1] neg_hi:[0,0,1]
	v_exp_f32_e32 v30, v30
	v_exp_f32_e32 v31, v31
	v_exp_f32_e32 v212, v24
	v_pk_add_f32 v[210:211], v[210:211], v[28:29]
	v_exp_f32_e32 v213, v25
	v_pk_add_f32 v[210:211], v[210:211], v[30:31]
	v_exp_f32_e32 v214, v26
	v_exp_f32_e32 v215, v27
	v_pk_add_f32 v[210:211], v[210:211], v[212:213]
	v_cvt_pk_bf16_f32 v24, v28, v29
	v_pk_add_f32 v[210:211], v[210:211], v[214:215]
	v_cvt_pk_bf16_f32 v25, v30, v31
	v_cvt_pk_bf16_f32 v26, v212, v213
	v_cvt_pk_bf16_f32 v27, v214, v215
	s_waitcnt lgkmcnt(4)
	s_nop 0
	v_mfma_f32_16x16x32_bf16 v[28:31], v[48:51], v[24:27], v[36:39]
	v_mfma_f32_16x16x32_bf16 v[36:39], v[64:67], v[24:27], v[44:47]
	v_mfma_f32_16x16x32_bf16 v[44:47], v[68:71], v[24:27], v[52:55]
	v_mfma_f32_16x16x32_bf16 v[24:27], v[170:173], v[24:27], v[32:35]
	s_nop 2
	ds_read_b128 v[32:35], v141 offset:32768
	ds_read_b128 v[48:51], v141 offset:40960
	ds_read_b128 v[52:55], v141 offset:49152
	ds_read_b128 v[64:67], v141 offset:57344
	v_pk_fma_f32 v[20:21], v[20:21], v[208:209], v[206:207] neg_lo:[0,0,1] neg_hi:[0,0,1]
	v_pk_fma_f32 v[22:23], v[22:23], v[208:209], v[206:207] neg_lo:[0,0,1] neg_hi:[0,0,1]
	v_exp_f32_e32 v20, v20
	v_pk_fma_f32 v[16:17], v[16:17], v[208:209], v[206:207] neg_lo:[0,0,1] neg_hi:[0,0,1]
	v_exp_f32_e32 v21, v21
	v_pk_fma_f32 v[18:19], v[18:19], v[208:209], v[206:207] neg_lo:[0,0,1] neg_hi:[0,0,1]
	v_exp_f32_e32 v22, v22
	v_exp_f32_e32 v23, v23
	v_exp_f32_e32 v212, v16
	v_pk_add_f32 v[210:211], v[210:211], v[20:21]
	v_exp_f32_e32 v213, v17
	v_pk_add_f32 v[210:211], v[210:211], v[22:23]
	v_exp_f32_e32 v214, v18
	v_exp_f32_e32 v215, v19
	v_pk_add_f32 v[210:211], v[210:211], v[212:213]
	v_cvt_pk_bf16_f32 v16, v20, v21
	v_pk_add_f32 v[210:211], v[210:211], v[214:215]
	v_cvt_pk_bf16_f32 v17, v22, v23
	v_cvt_pk_bf16_f32 v18, v212, v213
	v_cvt_pk_bf16_f32 v19, v214, v215
	s_waitcnt lgkmcnt(4)
	s_nop 0
	v_mfma_f32_16x16x32_bf16 v[20:23], v[40:43], v[16:19], v[28:31]
	v_mfma_f32_16x16x32_bf16 v[36:39], v[56:59], v[16:19], v[36:39]
	v_mfma_f32_16x16x32_bf16 v[40:43], v[60:63], v[16:19], v[44:47]
	v_mfma_f32_16x16x32_bf16 v[24:27], v[152:155], v[16:19], v[24:27]
	v_pk_fma_f32 v[12:13], v[12:13], v[208:209], v[206:207] neg_lo:[0,0,1] neg_hi:[0,0,1]
	v_pk_fma_f32 v[14:15], v[14:15], v[208:209], v[206:207] neg_lo:[0,0,1] neg_hi:[0,0,1]
	v_exp_f32_e32 v12, v12
	v_pk_fma_f32 v[8:9], v[8:9], v[208:209], v[206:207] neg_lo:[0,0,1] neg_hi:[0,0,1]
	v_exp_f32_e32 v13, v13
	v_pk_fma_f32 v[10:11], v[10:11], v[208:209], v[206:207] neg_lo:[0,0,1] neg_hi:[0,0,1]
	v_exp_f32_e32 v14, v14
	v_exp_f32_e32 v15, v15
	v_exp_f32_e32 v212, v8
	v_pk_add_f32 v[210:211], v[210:211], v[12:13]
	v_exp_f32_e32 v213, v9
	v_pk_add_f32 v[210:211], v[210:211], v[14:15]
	v_exp_f32_e32 v214, v10
	v_exp_f32_e32 v215, v11
	v_pk_add_f32 v[210:211], v[210:211], v[212:213]
	v_cvt_pk_bf16_f32 v44, v12, v13
	v_pk_add_f32 v[210:211], v[210:211], v[214:215]
	v_cvt_pk_bf16_f32 v45, v14, v15
	v_cvt_pk_bf16_f32 v46, v212, v213
	v_cvt_pk_bf16_f32 v47, v214, v215
	v_add_f32_e32 v28, v210, v211
	s_waitcnt lgkmcnt(0)
	v_mfma_f32_16x16x32_bf16 v[8:11], v[32:35], v[44:47], v[20:23]
	v_mfma_f32_16x16x32_bf16 v[12:15], v[48:51], v[44:47], v[36:39]
	v_mfma_f32_16x16x32_bf16 v[16:19], v[52:55], v[44:47], v[40:43]
	v_mfma_f32_16x16x32_bf16 v[20:23], v[64:67], v[44:47], v[24:27]
	s_andn2_b64 vcc, exec, s[74:75]
	s_mov_b64 s[68:69], -1
	s_cbranch_vccnz .LBB0_298
; __device__ __forceinline__ unsigned cvt_pk_bf16(float lo, float hi) { const f32x2 v = (f32x2){lo, hi}; return __builtin_bit_cast(unsigned, __builtin_convertvector(v, bf16v2)); }
; __device__ __forceinline__ void attn_store(bf16_t* MIX, int qtok, int h, int g, float lsum, const f32x4 (&o)[4]) {
;     lsum += __shfl_xor(lsum, 16); lsum += __shfl_xor(lsum, 32);
;     const float inv = 1.f / lsum;
;     bf16_t* op = MIX + (size_t)qtok * DM + 512 + h * 64 + 4 * g;
; #pragma unroll
;     for (int dt = 0; dt < 4; ++dt) { u32x2 w; w.x = cvt_pk_bf16(o[dt][0] * inv, o[dt][1] * inv); w.y = cvt_pk_bf16(o[dt][2] * inv, o[dt][3] * inv); *(u32x2*)(op + 16 * dt) = w; }
; }
; __device__ __forceinline__ void phase_mixer(const Params& p, LAS unsigned char* lds, int l, bool with_ctx, int G, int tid, int wave, int lane, int rep_attn, int rep_pool) {
;     ...
;                 if (ps == 0) attn_store(MIX, qtok, h, g, lA, oA);
	ds_bpermute_b32 v24, v114, v28
	v_ashrrev_i32_e32 v105, 31, v104
	s_waitcnt lgkmcnt(0)
	v_add_f32_e32 v24, v28, v24
	ds_bpermute_b32 v25, v115, v24
	s_waitcnt lgkmcnt(0)
	v_add_f32_e32 v24, v24, v25
	v_div_scale_f32 v25, s[68:69], v24, v24, 1.0
	v_rcp_f32_e32 v26, v25
	s_mov_b64 s[68:69], 0
	v_fma_f32 v27, -v25, v26, 1.0
	v_fmac_f32_e32 v26, v27, v26
	v_div_scale_f32 v27, vcc, 1.0, v24, 1.0
	v_mul_f32_e32 v29, v27, v26
	v_fma_f32 v30, -v25, v29, v27
	v_fmac_f32_e32 v29, v30, v26
	v_fma_f32 v25, -v25, v29, v27
	v_div_fmas_f32 v25, v25, v26, v29
	v_div_fixup_f32 v24, v25, v24, 1.0
	v_lshlrev_b64 v[26:27], 11, v[104:105]
	v_pk_mul_f32 v[30:31], v[8:9], v[24:25] op_sel_hi:[1,0]
	v_pk_mul_f32 v[32:33], v[10:11], v[24:25] op_sel_hi:[1,0]
	v_lshl_add_u64 v[26:27], v[102:103], 0, v[26:27]
	v_cvt_pk_bf16_f32 v30, v30, v31
	v_cvt_pk_bf16_f32 v31, v32, v33
	global_store_dwordx2 v[26:27], v[30:31], off offset:1024
	v_pk_mul_f32 v[30:31], v[12:13], v[24:25] op_sel_hi:[1,0]
	v_pk_mul_f32 v[32:33], v[14:15], v[24:25] op_sel_hi:[1,0]
	v_cvt_pk_bf16_f32 v30, v30, v31
	v_cvt_pk_bf16_f32 v31, v32, v33
	global_store_dwordx2 v[26:27], v[30:31], off offset:1056
	v_pk_mul_f32 v[30:31], v[16:17], v[24:25] op_sel_hi:[1,0]
	v_pk_mul_f32 v[32:33], v[18:19], v[24:25] op_sel_hi:[1,0]
	v_cvt_pk_bf16_f32 v30, v30, v31
	v_cvt_pk_bf16_f32 v31, v32, v33
	global_store_dwordx2 v[26:27], v[30:31], off offset:1088
	v_pk_mul_f32 v[30:31], v[20:21], v[24:25] op_sel_hi:[1,0]
	v_pk_mul_f32 v[24:25], v[22:23], v[24:25] op_sel_hi:[1,0]
	v_cvt_pk_bf16_f32 v30, v30, v31
	v_cvt_pk_bf16_f32 v31, v24, v25
	global_store_dwordx2 v[26:27], v[30:31], off offset:1120
	s_branch .LBB0_298
